# speedup vs baseline: 1.0035x; 1.0035x over previous
; #define LAS __attribute__((address_space(3)))
; #define ATT_KRD(KOFF, DLO, DHI) do { _Pragma("unroll") for (int d0 = (DLO); d0 < (DHI); ++d0) { kf[2 * d0] = *(const LAS bf16x8*)(lds + (KOFF) + kr + 2 * d0 * KCH); kf[2 * d0 + 1] = *(const LAS bf16x8*)(lds + (KOFF) + kr + 2 * d0 * KCH + 512); } } while (0)
; #define ATT_SB() __builtin_amdgcn_sched_barrier(0)
; #define ATT_EXP2(J) do { float e0_, e1_; if ((J) < 8) { e0_ = __builtin_amdgcn_exp2f(p0[2 * (J)]); e1_ = __builtin_amdgcn_exp2f(p0[2 * (J) + 1]); } else { e0_ = __builtin_amdgcn_exp2f(p1[2 * (J) - 16]); e1_ = __builtin_amdgcn_exp2f(p1[2 * (J) - 15]); } \
;                 sum += e0_; sum += e1_; asm volatile("" : "+v"(sum)); pkn[(J) >> 2][(J) & 3] = cvtpk_s(e0_, e1_); } while (0)
; __device__ __forceinline__ void attn_unit(LAS unsigned char* lds, bf16_t* Qm, const bf16_t* __restrict__ Kb, const bf16_t* __restrict__ Vt,
;                                           int b, int h, int qb, int lgS, float lam, float oscale, const float* __restrict__ subg, float* stash) {
;     ...
;             for (int ks = 1; ks < 4; ++ks) {
; #pragma unroll
;                 for (int blk = 0; blk < 4; ++blk) {
;                     const int gi = (ks - 1) * 4 + blk;
;                     if (blk == 0 && ks < 3) {
; #pragma unroll
;                         for (int b2 = 0; b2 < 4; ++b2) { const bf16x8 v_ = *(const LAS bf16x8*)(lds + vs0 + vr + b2 * 32 * VP + (ks + 1) * 32); if (ks & 1) vfa[b2] = v_; else vfb[b2] = v_; }
;                     }
;                     o[blk] = __builtin_amdgcn_mfma_f32_32x32x16_bf16((ks & 1) ? vfb[blk] : vfa[blk], __builtin_bit_cast(bf16x8, pk[ks]), o[blk], 0, 0, 0);
;                     ATT_EXP2(gi);
;                     if (gi < 4) ATT_EXP2(12 + gi);
;                     ATT_SB();
;                 }
;             }
;     ...
;             lrun += sum;
; #pragma unroll
;             for (int j = 0; j < 4; ++j) pk[j] = pkn[j];
;             if (t + 2 < NT) ATT_KRD(kq2, 0, 1);
; #pragma unroll
;             for (int b2 = 0; b2 < 4; ++b2) vfa[b2] = *(const LAS bf16x8*)(lds + vs1 + vr + b2 * 32 * VP);
;             ATT_SB();
;             { const int tmp = vs0; vs0 = vs1; vs1 = vs2; vs2 = tmp; }
;             { const int tmp = kq0; kq0 = kq1; kq1 = kq2; kq2 = tmp; }
;             __syncthreads();
.LBB0_342:
	v_exp_f32_e32 v96, v96
	s_waitcnt lgkmcnt(3)
	v_mfma_f32_32x32x16_bf16 v[0:15], v[216:219], v[180:183], v[0:15]
	v_exp_f32_e32 v97, v97
	ds_read_b128 v[192:195], v251 offset:25408
	ds_read_b128 v[196:199], v251 offset:30016
	ds_read_b128 v[188:191], v251 offset:34624
	ds_read_b128 v[184:187], v251 offset:39232
	v_exp_f32_e32 v88, v88
	v_add_f32_e32 v200, 0, v96
	v_exp_f32_e32 v89, v89
	v_add_f32_e32 v200, v97, v200
	s_nop 0
	v_add_f32_e32 v200, v88, v200
	v_add_f32_e32 v200, v89, v200
	v_exp_f32_e32 v98, v98
	s_waitcnt lgkmcnt(6)
	v_mfma_f32_32x32x16_bf16 v[48:63], v[212:215], v[180:183], v[48:63]
	v_exp_f32_e32 v99, v99
	v_exp_f32_e32 v90, v90
	v_add_f32_e32 v200, v98, v200
	v_exp_f32_e32 v91, v91
	v_add_f32_e32 v200, v99, v200
	s_nop 0
	v_add_f32_e32 v200, v90, v200
	v_add_f32_e32 v200, v91, v200
	v_exp_f32_e32 v100, v100
	s_waitcnt lgkmcnt(5)
	v_mfma_f32_32x32x16_bf16 v[32:47], v[208:211], v[180:183], v[32:47]
	v_exp_f32_e32 v101, v101
	v_exp_f32_e32 v92, v92
	v_add_f32_e32 v200, v100, v200
	v_exp_f32_e32 v93, v93
	v_add_f32_e32 v200, v101, v200
	s_nop 0
	v_add_f32_e32 v200, v92, v200
	v_add_f32_e32 v200, v93, v200
	v_exp_f32_e32 v102, v102
	s_waitcnt lgkmcnt(4)
	v_mfma_f32_32x32x16_bf16 v[16:31], v[204:207], v[180:183], v[16:31]
	v_exp_f32_e32 v103, v103
	v_exp_f32_e32 v94, v94
	v_add_f32_e32 v180, v102, v200
	v_exp_f32_e32 v95, v95
	v_add_f32_e32 v180, v103, v180
	s_nop 0
	v_add_f32_e32 v180, v94, v180
	v_add_f32_e32 v212, v95, v180
	s_waitcnt lgkmcnt(3)
	v_mfma_f32_32x32x16_bf16 v[0:15], v[192:195], v[172:175], v[0:15]
	ds_read_b128 v[180:183], v251 offset:25440
	ds_read_b128 v[200:203], v251 offset:30048
	ds_read_b128 v[204:207], v251 offset:34656
	ds_read_b128 v[208:211], v251 offset:39264
	v_exp_f32_e32 v104, v104
	v_exp_f32_e32 v105, v105
	v_add_f32_e32 v156, v104, v212
	v_add_f32_e32 v156, v105, v156
	v_add_u32_e32 v251, s25, v220
	v_add_u32_e32 v160, s50, v235
	s_waitcnt lgkmcnt(6)
	v_mfma_f32_32x32x16_bf16 v[48:63], v[196:199], v[172:175], v[48:63]
	ds_read_b128 v[192:195], v251 offset:29952
	v_exp_f32_e32 v106, v106
	v_exp_f32_e32 v107, v107
	v_add_f32_e32 v156, v106, v156
	v_add_f32_e32 v156, v107, v156
	s_waitcnt lgkmcnt(6)
	v_mfma_f32_32x32x16_bf16 v[32:47], v[188:191], v[172:175], v[32:47]
	ds_read_b128 v[196:199], v251 offset:25344
	v_exp_f32_e32 v108, v108
	v_exp_f32_e32 v109, v109
	v_add_f32_e32 v156, v108, v156
	v_add_f32_e32 v156, v109, v156
	s_waitcnt lgkmcnt(6)
	v_mfma_f32_32x32x16_bf16 v[16:31], v[184:187], v[172:175], v[16:31]
	ds_read_b128 v[188:191], v251 offset:34560
	ds_read_b128 v[212:215], v160 offset:4224
	ds_read_b128 v[216:219], v160 offset:4736
	v_exp_f32_e32 v110, v110
	v_exp_f32_e32 v111, v111
	v_add_f32_e32 v156, v110, v156
	v_add_f32_e32 v156, v111, v156
	s_waitcnt lgkmcnt(8)
	v_mfma_f32_32x32x16_bf16 v[0:15], v[180:183], v[164:167], v[0:15]
	ds_read_b128 v[184:187], v251 offset:39168
	ds_read_b128 v[222:225], v160 offset:6336
	ds_read_b128 v[240:243], v160 offset:6848
	v_exp_f32_e32 v80, v80
	v_exp_f32_e32 v81, v81
	v_add_f32_e32 v156, v80, v156
	v_add_f32_e32 v156, v81, v156
	v_cvt_pk_bf16_f32 v180, v104, v105
	v_cvt_pk_bf16_f32 v181, v106, v107
	v_cvt_pk_bf16_f32 v182, v108, v109
	v_cvt_pk_bf16_f32 v183, v110, v111
	s_waitcnt lgkmcnt(10)
	v_mfma_f32_32x32x16_bf16 v[48:63], v[200:203], v[164:167], v[48:63]
	v_exp_f32_e32 v82, v82
	v_exp_f32_e32 v83, v83
	v_add_f32_e32 v156, v82, v156
	v_add_f32_e32 v156, v83, v156
	v_cvt_pk_bf16_f32 v200, v96, v97
	v_cvt_pk_bf16_f32 v201, v98, v99
	v_cvt_pk_bf16_f32 v202, v100, v101
	v_cvt_pk_bf16_f32 v203, v102, v103
	v_cvt_pk_bf16_f32 v172, v80, v81
	s_waitcnt lgkmcnt(9)
	v_mfma_f32_32x32x16_bf16 v[32:47], v[204:207], v[164:167], v[32:47]
	ds_read_b128 v[204:207], v160 offset:2112
	v_exp_f32_e32 v84, v84
	v_exp_f32_e32 v85, v85
	v_add_f32_e32 v156, v84, v156
	v_add_f32_e32 v156, v85, v156
	v_cvt_pk_bf16_f32 v173, v82, v83
	s_waitcnt lgkmcnt(9)
	v_mfma_f32_32x32x16_bf16 v[16:31], v[208:211], v[164:167], v[16:31]
	ds_read_b128 v[208:211], v160 offset:2624
	v_exp_f32_e32 v86, v86
	v_exp_f32_e32 v87, v87
	v_add_f32_e32 v156, v86, v156
	v_add_f32_e32 v156, v87, v156
	v_add_f32_e32 v249, v249, v156
	ds_read_b128 v[156:159], v160
	ds_read_b128 v[160:163], v160 offset:512
	v_cvt_pk_bf16_f32 v174, v84, v85
	v_cvt_pk_bf16_f32 v175, v86, v87
	v_cvt_pk_bf16_f32 v164, v88, v89
	v_cvt_pk_bf16_f32 v165, v90, v91
	v_cvt_pk_bf16_f32 v166, v92, v93
	v_cvt_pk_bf16_f32 v167, v94, v95
	s_add_i32 s57, s57, 1
	s_add_i32 s90, s90, 64
	s_mov_b64 s[28:29], 0x10000
	v_lshl_add_u64 v[238:239], v[238:239], 0, s[28:29]
	s_waitcnt lgkmcnt(0)
	s_barrier
	s_cmp_eq_u32 s63, s57
	s_cbranch_scc1 .LBB0_349
	s_mov_b32 s28, s25
	s_mov_b32 s25, s56
	s_mov_b32 s29, s60
	s_mov_b32 s60, s61
	s_mov_b32 s56, s65
	s_branch .LBB0_335
